# B far loop: row-sum pk_add chain and lsum update moved from after the tile barrier into the second PV MFMA block (MFMA shadow; strategy 8 interleave)
# speedup vs baseline: 1.0015x; 1.0015x over previous
; template <int DQK, bool MB> ...
;     ...
;                 for (int ks = 0; ks < 4; ++ks)
; #pragma unroll
;                     for (int j = 0; j < 4; ++j) { const float p = __builtin_amdgcn_exp2f(s[ks][ct][j] - mnew); s[ks][ct][j] = p; ps += p; }
;                 lsum[ct] = lsum[ct] * alpha + ps; alpha2[ct] = alpha;
;             }
;             {
; #pragma unroll
;                 for (int ct = 0; ct < 2; ++ct)
; #pragma unroll
;                     for (int dt = 0; dt < 8; ++dt) o[ct][dt] *= alpha2[ct];
;             }
; #pragma unroll
;             for (int kb2 = 0; kb2 < 2; ++kb2) {
;                 bf16x8 pb[2];
; #pragma unroll
;                 for (int ct = 0; ct < 2; ++ct) { u32x4 w; w.x = pk2(s[2 * kb2][ct][0], s[2 * kb2][ct][1]); w.y = pk2(s[2 * kb2][ct][2], s[2 * kb2][ct][3]);
;                     w.z = pk2(s[2 * kb2 + 1][ct][0], s[2 * kb2 + 1][ct][1]); w.w = pk2(s[2 * kb2 + 1][ct][2], s[2 * kb2 + 1][ct][3]); pb[ct] = __builtin_bit_cast(bf16x8, w); }
;                 bf16x8 vf[8];
; #pragma unroll
;                 for (int dt = 0; dt < 8; ++dt) { const LAS unsigned char* vp = vb + (16 * dt + r) * VT_PITCH + (32 * kb2 + 4 * q) * 2;
;                     const s16x4 lo = *(const LAS s16x4*)vp, hi = *(const LAS s16x4*)(vp + 32);
;                     vf[dt] = __builtin_shufflevector(lo, hi, 0, 1, 2, 3, 4, 5, 6, 7); }
;                 __builtin_amdgcn_sched_barrier(0);
; #pragma unroll
;                 for (int dt = 0; dt < 8; ++dt) {
;                     o[0][dt] = __builtin_amdgcn_mfma_f32_16x16x32_bf16(vf[dt], pb[0], o[0][dt], 0, 0, 0);
;                     o[1][dt] = __builtin_amdgcn_mfma_f32_16x16x32_bf16(vf[dt], pb[1], o[1][dt], 0, 0, 0); }
;                 __builtin_amdgcn_sched_barrier(0);
;             }
;         }
;         if (pre) { const int nb = ST ? ((buf == 0) ? 2 : buf - 1) : (buf ^ 1); LAS unsigned char* kbn = kbase + nb * KT_BYTES; LAS unsigned char* vbn = vbase + nb * VT_BYTES;
; #pragma unroll
;             for (int i = 0; i < KCH; ++i) *(LAS u32x4*)(kbn + klo0 + 2048 * i) = kreg[i];
; #pragma unroll
;             for (int i = 0; i < 2; ++i) { *(LAS u32x2*)(vbn + vlo0 + 64 * VT_PITCH * i) = (u32x2){vreg[i].x, vreg[i].y}; *(LAS u32x2*)(vbn + vlo0 + 64 * VT_PITCH * i + 8) = (u32x2){vreg[i].z, vreg[i].w}; } }
;         __syncthreads();
;         buf = ST ? ((buf == 2) ? 0 : buf + 1) : (buf ^ 1);
.Llazy_bf_skip:
	ds_read2_b64 v[190:193], v185 offset1:4
	ds_read2_b64 v[194:197], v222 offset0:16 offset1:20
	ds_read2_b64 v[198:201], v223 offset0:32 offset1:36
	ds_read2_b64 v[202:205], v225 offset0:48 offset1:52
	ds_read2_b64 v[206:209], v230 offset0:64 offset1:68
	ds_read2_b64 v[210:213], v231 offset0:80 offset1:84
	ds_read2_b64 v[214:217], v232 offset0:96 offset1:100
	ds_read2_b64 v[218:221], v169 offset0:112 offset1:116
	v_cvt_pk_bf16_f32 v186, v157, v143
	v_cvt_pk_bf16_f32 v187, v141, v139
	v_cvt_pk_bf16_f32 v188, v137, v135
	v_cvt_pk_bf16_f32 v189, v133, v131
	v_cvt_pk_bf16_f32 v226, v156, v142
	v_cvt_pk_bf16_f32 v227, v140, v138
	v_cvt_pk_bf16_f32 v228, v136, v134
	v_cvt_pk_bf16_f32 v229, v132, v130
	s_waitcnt lgkmcnt(7)
	v_mfma_f32_16x16x32_bf16 v[108:111], v[190:193], v[186:189], v[108:111]
	v_mfma_f32_16x16x32_bf16 v[28:31], v[190:193], v[226:229], v[28:31]
	s_waitcnt lgkmcnt(6)
	v_mfma_f32_16x16x32_bf16 v[104:107], v[194:197], v[186:189], v[104:107]
	v_mfma_f32_16x16x32_bf16 v[24:27], v[194:197], v[226:229], v[24:27]
	s_waitcnt lgkmcnt(5)
	v_mfma_f32_16x16x32_bf16 v[100:103], v[198:201], v[186:189], v[100:103]
	v_mfma_f32_16x16x32_bf16 v[20:23], v[198:201], v[226:229], v[20:23]
	s_waitcnt lgkmcnt(4)
	v_mfma_f32_16x16x32_bf16 v[96:99], v[202:205], v[186:189], v[96:99]
	v_mfma_f32_16x16x32_bf16 v[16:19], v[202:205], v[226:229], v[16:19]
	s_waitcnt lgkmcnt(3)
	v_mfma_f32_16x16x32_bf16 v[84:87], v[206:209], v[186:189], v[84:87]
	v_mfma_f32_16x16x32_bf16 v[12:15], v[206:209], v[226:229], v[12:15]
	s_waitcnt lgkmcnt(2)
	v_mfma_f32_16x16x32_bf16 v[40:43], v[210:213], v[186:189], v[40:43]
	v_mfma_f32_16x16x32_bf16 v[8:11], v[210:213], v[226:229], v[8:11]
	s_waitcnt lgkmcnt(1)
	v_mfma_f32_16x16x32_bf16 v[36:39], v[214:217], v[186:189], v[36:39]
	v_mfma_f32_16x16x32_bf16 v[4:7], v[214:217], v[226:229], v[4:7]
	s_waitcnt lgkmcnt(0)
	v_mfma_f32_16x16x32_bf16 v[32:35], v[218:221], v[186:189], v[32:35]
	v_mfma_f32_16x16x32_bf16 v[0:3], v[218:221], v[226:229], v[0:3]
	ds_read2_b64 v[190:193], v185 offset0:8 offset1:12
	ds_read2_b64 v[194:197], v222 offset0:24 offset1:28
	ds_read2_b64 v[198:201], v223 offset0:40 offset1:44
	ds_read2_b64 v[202:205], v225 offset0:56 offset1:60
	ds_read2_b64 v[206:209], v230 offset0:72 offset1:76
	ds_read2_b64 v[210:213], v231 offset0:88 offset1:92
	ds_read2_b64 v[214:217], v232 offset0:104 offset1:108
	ds_read2_b64 v[218:221], v169 offset0:120 offset1:124
	v_cvt_pk_bf16_f32 v186, v129, v127
	v_cvt_pk_bf16_f32 v187, v125, v123
	v_cvt_pk_bf16_f32 v188, v165, v161
	v_cvt_pk_bf16_f32 v189, v167, v163
	v_cvt_pk_bf16_f32 v226, v128, v126
	v_cvt_pk_bf16_f32 v227, v124, v122
	v_cvt_pk_bf16_f32 v228, v164, v160
	v_cvt_pk_bf16_f32 v229, v166, v162
	s_waitcnt lgkmcnt(7)
	v_mfma_f32_16x16x32_bf16 v[108:111], v[190:193], v[186:189], v[108:111]
	v_pk_add_f32 v[156:157], v[156:157], 0 op_sel_hi:[1,0]
	v_mfma_f32_16x16x32_bf16 v[28:31], v[190:193], v[226:229], v[28:31]
	v_pk_add_f32 v[142:143], v[142:143], v[156:157]
	s_waitcnt lgkmcnt(6)
	v_mfma_f32_16x16x32_bf16 v[104:107], v[194:197], v[186:189], v[104:107]
	v_pk_add_f32 v[140:141], v[140:141], v[142:143]
	v_mfma_f32_16x16x32_bf16 v[24:27], v[194:197], v[226:229], v[24:27]
	v_pk_add_f32 v[138:139], v[138:139], v[140:141]
	s_waitcnt lgkmcnt(5)
	v_mfma_f32_16x16x32_bf16 v[100:103], v[198:201], v[186:189], v[100:103]
	v_pk_add_f32 v[136:137], v[136:137], v[138:139]
	v_mfma_f32_16x16x32_bf16 v[20:23], v[198:201], v[226:229], v[20:23]
	v_pk_add_f32 v[134:135], v[134:135], v[136:137]
	s_waitcnt lgkmcnt(4)
	v_mfma_f32_16x16x32_bf16 v[96:99], v[202:205], v[186:189], v[96:99]
	v_pk_add_f32 v[132:133], v[132:133], v[134:135]
	v_mfma_f32_16x16x32_bf16 v[16:19], v[202:205], v[226:229], v[16:19]
	v_pk_add_f32 v[130:131], v[130:131], v[132:133]
	s_waitcnt lgkmcnt(3)
	v_mfma_f32_16x16x32_bf16 v[84:87], v[206:209], v[186:189], v[84:87]
	v_pk_add_f32 v[128:129], v[128:129], v[130:131]
	v_mfma_f32_16x16x32_bf16 v[12:15], v[206:209], v[226:229], v[12:15]
	v_pk_add_f32 v[126:127], v[126:127], v[128:129]
	s_waitcnt lgkmcnt(2)
	v_mfma_f32_16x16x32_bf16 v[40:43], v[210:213], v[186:189], v[40:43]
	v_pk_add_f32 v[124:125], v[124:125], v[126:127]
	v_mfma_f32_16x16x32_bf16 v[8:11], v[210:213], v[226:229], v[8:11]
	v_pk_add_f32 v[122:123], v[122:123], v[124:125]
	s_waitcnt lgkmcnt(1)
	v_mfma_f32_16x16x32_bf16 v[36:39], v[214:217], v[186:189], v[36:39]
	v_pk_add_f32 v[122:123], v[164:165], v[122:123]
	v_mfma_f32_16x16x32_bf16 v[4:7], v[214:217], v[226:229], v[4:7]
	v_pk_add_f32 v[122:123], v[160:161], v[122:123]
	s_waitcnt lgkmcnt(0)
	v_mfma_f32_16x16x32_bf16 v[32:35], v[218:221], v[186:189], v[32:35]
	v_pk_add_f32 v[122:123], v[166:167], v[122:123]
	v_mfma_f32_16x16x32_bf16 v[0:3], v[218:221], v[226:229], v[0:3]
	v_pk_add_f32 v[122:123], v[162:163], v[122:123]
	v_mov_b32_e32 v169, v158
	s_nop 0
	v_pk_fma_f32 v[148:149], v[148:149], v[168:169], v[122:123]
	s_andn2_b64 vcc, exec, s[0:1]
	s_xor_b32 s45, s45, 1
	s_cbranch_vccnz .LBB0_667
	v_lshl_add_u32 v169, s45, 14, v178
	s_mul_i32 s0, s45, 0x4400
	s_waitcnt vmcnt(3)
	ds_write_b128 v169, v[48:51]
	s_waitcnt vmcnt(2)
	ds_write_b128 v169, v[52:55] offset:2048
	v_add_u32_e32 v169, s0, v177
	v_add_u32_e32 v185, 0x8000, v169
	v_add_u32_e32 v169, 0xa200, v169
	s_waitcnt vmcnt(1)
	ds_write2_b64 v185, v[88:89], v[90:91] offset1:1
	s_waitcnt vmcnt(0)
	ds_write2_b64 v169, v[92:93], v[94:95] offset1:1
.LBB0_667:
	s_add_i32 s4, s4, 8
	s_add_i32 s10, s10, 64
	s_cmp_eq_u32 s46, s5
	v_lshl_add_u64 v[120:121], v[120:121], 0, s[20:21]
	s_waitcnt lgkmcnt(0)
	s_barrier
	s_cbranch_scc1 .LBB0_672
	v_mov_b32_e32 v122, v183
	v_mov_b32_e32 v123, v182
	s_branch .LBB0_663
